# sweep 2 far tiles: PV(keys 32-63) V operands read during the preceding softmax segment into the dead QK operand registers
# baseline (speedup 1.0000x reference)
; #define SBAR() __builtin_amdgcn_sched_barrier(0)
; template <bool DIFF> ...
;     ...
;       qkt<DIFF>(a0, b0, K_lds, Q_lds, r32, r32, hi);
;       qkt<DIFF>(a1, b1, K_lds, Q_lds, r32 + 32, r32, hi);
;       SBAR();
;     ...
;       BIAS_APPLY(t, 0, a0, b0, cb0);
;       { const float x1 = fmaf(cb0, C, e1), x2 = fmaf(cb0, C, e2);
; #pragma unroll
;       for (int r = 0; r < 16; ++r) a0[r] = __builtin_amdgcn_exp2f(fmaf(a0[r], C, x1));
;       if (DIFF) {
; #pragma unroll
;         for (int r = 0; r < 16; ++r) a0[r] = fmaf(nsg, __builtin_amdgcn_exp2f(fmaf(b0[r], C, x2)), a0[r]);
;       } }
;       PK4(a0, 0, pa0); PK4(a0, 8, pa1);
.Lsw2f:
	ds_read_b128 v[64:67], v176
	ds_read_b128 v[68:71], v172 offset:36864
	ds_read_b128 v[72:75], v177
	ds_read_b128 v[76:79], v176 offset:8192
	s_waitcnt lgkmcnt(2)
	v_mfma_f32_32x32x16_bf16 v[112:127], v[64:67], v[68:71], 0
	ds_read_b128 v[64:67], v171 offset:36864
	ds_read_b128 v[128:131], v177 offset:8192
	s_waitcnt lgkmcnt(1)
	v_mfma_f32_32x32x16_bf16 v[96:111], v[72:75], v[64:67], 0
	ds_read_b128 v[72:75], v178
	ds_read_b128 v[132:135], v170 offset:36864
	ds_read_b128 v[80:83], v179
	ds_read_b128 v[136:139], v178 offset:8192
	ds_read_b128 v[140:143], v169 offset:36864
	ds_read_b128 v[192:195], v179 offset:8192
	s_waitcnt lgkmcnt(1)
	v_mfma_f32_32x32x16_bf16 v[96:111], v[80:83], v[140:143], v[96:111]
	v_mfma_f32_32x32x16_bf16 v[112:127], v[72:75], v[132:135], v[112:127]
	ds_read_b128 v[72:75], v180
	ds_read_b128 v[196:199], v168 offset:36864
	ds_read_b128 v[80:83], v181
	ds_read_b128 v[200:203], v180 offset:8192
	ds_read_b128 v[204:207], v167 offset:36864
	ds_read_b128 v[210:213], v181 offset:8192
	s_waitcnt lgkmcnt(1)
	v_mfma_f32_32x32x16_bf16 v[96:111], v[80:83], v[204:207], v[96:111]
	v_mfma_f32_32x32x16_bf16 v[112:127], v[72:75], v[196:199], v[112:127]
	ds_read_b128 v[72:75], v182
	ds_read_b128 v[214:217], v166 offset:36864
	ds_read_b128 v[80:83], v183
	ds_read_b128 v[218:221], v182 offset:8192
	ds_read_b128 v[222:225], v149 offset:36864
	ds_read_b128 v[226:229], v183 offset:8192
	s_waitcnt lgkmcnt(1)
	v_mfma_f32_32x32x16_bf16 v[96:111], v[80:83], v[222:225], v[96:111]
	v_mfma_f32_32x32x16_bf16 v[112:127], v[72:75], v[214:217], v[112:127]
	s_waitcnt lgkmcnt(0)
	v_mfma_f32_32x32x16_bf16 v[80:95], v[76:79], v[68:71], 0
	v_fmamk_f32 v235, v234, 0x3e38aa3b, v188
	v_fmamk_f32 v234, v234, 0x3e38aa3b, v187
	s_nop 8
	v_fmamk_f32 v112, v112, 0x3e38aa3b, v235
	v_fmamk_f32 v113, v113, 0x3e38aa3b, v235
	v_fmamk_f32 v114, v114, 0x3e38aa3b, v235
	v_fmamk_f32 v115, v115, 0x3e38aa3b, v235
	v_fmamk_f32 v116, v116, 0x3e38aa3b, v235
	v_fmamk_f32 v117, v117, 0x3e38aa3b, v235
	v_fmamk_f32 v96, v96, 0x3e38aa3b, v234
	v_fmamk_f32 v97, v97, 0x3e38aa3b, v234
	v_fmamk_f32 v98, v98, 0x3e38aa3b, v234
	v_fmamk_f32 v99, v99, 0x3e38aa3b, v234
	v_fmamk_f32 v100, v100, 0x3e38aa3b, v234
	v_fmamk_f32 v101, v101, 0x3e38aa3b, v234
	v_exp_f32_e32 v112, v112
	v_mfma_f32_32x32x16_bf16 v[64:79], v[128:131], v[64:67], 0
	v_exp_f32_e32 v113, v113
	v_exp_f32_e32 v114, v114
	v_exp_f32_e32 v115, v115
	v_exp_f32_e32 v116, v116
	v_exp_f32_e32 v117, v117
	v_fmamk_f32 v118, v118, 0x3e38aa3b, v235
	v_fmamk_f32 v119, v119, 0x3e38aa3b, v235
	v_fmamk_f32 v120, v120, 0x3e38aa3b, v235
	v_fmamk_f32 v121, v121, 0x3e38aa3b, v235
	v_fmamk_f32 v122, v122, 0x3e38aa3b, v235
	v_mfma_f32_32x32x16_bf16 v[80:95], v[136:139], v[132:135], v[80:95]
	v_fmamk_f32 v123, v123, 0x3e38aa3b, v235
	v_fmamk_f32 v124, v124, 0x3e38aa3b, v235
	v_fmamk_f32 v125, v125, 0x3e38aa3b, v235
	v_fmamk_f32 v126, v126, 0x3e38aa3b, v235
	v_fmac_f32_e32 v235, 0x3e38aa3b, v127
	v_exp_f32_e32 v96, v96
	v_exp_f32_e32 v97, v97
	v_exp_f32_e32 v98, v98
	v_exp_f32_e32 v99, v99
	v_exp_f32_e32 v100, v100
	v_exp_f32_e32 v101, v101
	v_mfma_f32_32x32x16_bf16 v[64:79], v[192:195], v[140:143], v[64:79]
	v_lshl_add_u64 v[128:129], v[150:151], 0, s[34:35]
	v_add_co_u32_e32 v130, vcc, s70, v128
	s_nop 1
	v_addc_co_u32_e32 v131, vcc, 0, v129, vcc
	v_add_co_u32_e32 v132, vcc, s71, v128
	v_lshl_add_u64 v[136:137], v[152:153], 0, s[34:35]
	s_nop 0
	v_addc_co_u32_e32 v133, vcc, 0, v129, vcc
	v_add_co_u32_e32 v138, vcc, s72, v136
	s_nop 1
	v_addc_co_u32_e32 v139, vcc, 0, v137, vcc
	v_add_co_u32_e32 v140, vcc, s73, v136
	global_load_dwordx4 v[128:131], v[130:131], off
	s_nop 0
	global_load_dwordx4 v[132:135], v[132:133], off
	v_addc_co_u32_e32 v141, vcc, 0, v137, vcc
	global_load_dwordx4 v[136:139], v[138:139], off
	s_nop 0
	global_load_dwordx4 v[140:143], v[140:141], off
	v_fmamk_f32 v102, v102, 0x3e38aa3b, v234
	v_fmamk_f32 v103, v103, 0x3e38aa3b, v234
	v_fmamk_f32 v104, v104, 0x3e38aa3b, v234
	v_fmamk_f32 v105, v105, 0x3e38aa3b, v234
	v_fmamk_f32 v106, v106, 0x3e38aa3b, v234
	v_fmamk_f32 v107, v107, 0x3e38aa3b, v234
	v_fmamk_f32 v108, v108, 0x3e38aa3b, v234
	v_fmamk_f32 v109, v109, 0x3e38aa3b, v234
	v_fmamk_f32 v110, v110, 0x3e38aa3b, v234
	v_fmac_f32_e32 v234, 0x3e38aa3b, v111
	v_exp_f32_e32 v118, v118
	v_exp_f32_e32 v119, v119
	v_exp_f32_e32 v120, v120
	v_mfma_f32_32x32x16_bf16 v[80:95], v[200:203], v[196:199], v[80:95]
	v_exp_f32_e32 v121, v121
	v_exp_f32_e32 v122, v122
	v_exp_f32_e32 v123, v123
	v_exp_f32_e32 v124, v124
	v_exp_f32_e32 v125, v125
	v_exp_f32_e32 v126, v126
	v_exp_f32_e32 v127, v235
	v_exp_f32_e32 v102, v102
	v_mfma_f32_32x32x16_bf16 v[64:79], v[210:213], v[204:207], v[64:79]
	v_exp_f32_e32 v103, v103
	v_exp_f32_e32 v104, v104
	v_exp_f32_e32 v105, v105
	v_exp_f32_e32 v106, v106
	v_exp_f32_e32 v107, v107
	v_exp_f32_e32 v108, v108
	v_exp_f32_e32 v109, v109
	v_exp_f32_e32 v110, v110
	v_mfma_f32_32x32x16_bf16 v[80:95], v[218:221], v[214:217], v[80:95]
	v_exp_f32_e32 v111, v234
	v_pk_fma_f32 v[96:97], v[144:145], v[96:97], v[112:113]
	v_pk_fma_f32 v[98:99], v[144:145], v[98:99], v[114:115]
	v_pk_fma_f32 v[100:101], v[144:145], v[100:101], v[116:117]
	v_pk_fma_f32 v[102:103], v[144:145], v[102:103], v[118:119]
	v_pk_fma_f32 v[104:105], v[144:145], v[104:105], v[120:121]
	v_pk_fma_f32 v[106:107], v[144:145], v[106:107], v[122:123]
	v_pk_fma_f32 v[108:109], v[144:145], v[108:109], v[124:125]
	v_mfma_f32_32x32x16_bf16 v[64:79], v[226:229], v[222:225], v[64:79]
	v_pk_fma_f32 v[110:111], v[144:145], v[110:111], v[126:127]
	v_cvt_pk_bf16_f32 v96, v96, v97
	v_cvt_pk_bf16_f32 v97, v98, v99
	v_cvt_pk_bf16_f32 v98, v100, v101
; #define SBAR() __builtin_amdgcn_sched_barrier(0)
; template <int KS> __device__ __forceinline__ void pv_step(f32x16* o, int vb, bf16x8 pa) {
;   const s16x4 l0 = tr_read<v_rd_off(0, KS, 0)>(vb), h0 = tr_read<v_rd_off(0, KS, 1)>(vb), l1 = tr_read<v_rd_off(1, KS, 0)>(vb), h1 = tr_read<v_rd_off(1, KS, 1)>(vb);
;   const s16x4 l2 = tr_read<v_rd_off(2, KS, 0)>(vb), h2 = tr_read<v_rd_off(2, KS, 1)>(vb), l3 = tr_read<v_rd_off(3, KS, 0)>(vb), h3 = tr_read<v_rd_off(3, KS, 1)>(vb);
;   asm volatile("s_waitcnt lgkmcnt(0)" ::: "memory"); SBAR();
;     ...
;   o[0] = __builtin_amdgcn_mfma_f32_32x32x16_bf16(pa, PK(l0, h0), o[0], 0, 0, 0);
;   o[1] = __builtin_amdgcn_mfma_f32_32x32x16_bf16(pa, PK(l1, h1), o[1], 0, 0, 0);
;   o[2] = __builtin_amdgcn_mfma_f32_32x32x16_bf16(pa, PK(l2, h2), o[2], 0, 0, 0);
;   o[3] = __builtin_amdgcn_mfma_f32_32x32x16_bf16(pa, PK(l3, h3), o[3], 0, 0, 0);
;     ...
; }
; template <bool DIFF> ...
;     ...
;       PK4(a0, 0, pa0); PK4(a0, 8, pa1);
;       SBAR();
;       pv_step<0>(o, vb0, pa0); pv_step<1>(o, vb0, pa1);
;       SBAR();
;       BIAS_APPLY(t, 1, a1, b1, cb1);
;       { const float x1 = fmaf(cb1, C, e1), x2 = fmaf(cb1, C, e2);
; #pragma unroll
;       for (int r = 0; r < 16; ++r) a1[r] = __builtin_amdgcn_exp2f(fmaf(a1[r], C, x1));
;       if (DIFF) {
; #pragma unroll
;         for (int r = 0; r < 16; ++r) a1[r] = fmaf(nsg, __builtin_amdgcn_exp2f(fmaf(b1[r], C, x2)), a1[r]);
;       } }
;       PK4(a1, 0, pa2); PK4(a1, 8, pa3);
;       SBAR();
;       pv_step<2>(o, vb0, pa2); pv_step<3>(o, vb0, pa3);
	v_cvt_pk_bf16_f32 v99, v102, v103
	s_nop 0
	v_permlane32_swap_b32_e32 v96, v98
	v_cvt_pk_bf16_f32 v100, v104, v105
	v_cvt_pk_bf16_f32 v101, v106, v107
	v_cvt_pk_bf16_f32 v102, v108, v109
	v_cvt_pk_bf16_f32 v103, v110, v111
	v_permlane32_swap_b32_e32 v97, v99
	v_permlane32_swap_b32_e32 v100, v102
	v_permlane32_swap_b32_e32 v101, v103
	ds_read_b64_tr_b16 v[104:105], v146 offset:0
	ds_read_b64_tr_b16 v[106:107], v146 offset:0x800
	ds_read_b64_tr_b16 v[108:109], v146 offset:0x200
	ds_read_b64_tr_b16 v[110:111], v146 offset:0xa00
	ds_read_b64_tr_b16 v[112:113], v146 offset:0x400
	ds_read_b64_tr_b16 v[114:115], v146 offset:0xc00
	ds_read_b64_tr_b16 v[116:117], v146 offset:0x600
	ds_read_b64_tr_b16 v[118:119], v146 offset:0xe00
	ds_read_b64_tr_b16 v[238:239], v146 offset:0x1000
	ds_read_b64_tr_b16 v[240:241], v146 offset:0x1800
	ds_read_b64_tr_b16 v[242:243], v146 offset:0x1200
	ds_read_b64_tr_b16 v[244:245], v146 offset:0x1a00
	ds_read_b64_tr_b16 v[246:247], v146 offset:0x1400
	ds_read_b64_tr_b16 v[248:249], v146 offset:0x1c00
	ds_read_b64_tr_b16 v[120:121], v146 offset:0x1600
	ds_read_b64_tr_b16 v[122:123], v146 offset:0x1e00
	v_fmamk_f32 v237, v236, 0x3e38aa3b, v188
	v_fmamk_f32 v236, v236, 0x3e38aa3b, v187
	v_fmamk_f32 v80, v80, 0x3e38aa3b, v237
	v_fmamk_f32 v81, v81, 0x3e38aa3b, v237
	v_fmamk_f32 v82, v82, 0x3e38aa3b, v237
	v_fmamk_f32 v83, v83, 0x3e38aa3b, v237
	v_fmamk_f32 v84, v84, 0x3e38aa3b, v237
	v_fmamk_f32 v85, v85, 0x3e38aa3b, v237
	v_fmamk_f32 v86, v86, 0x3e38aa3b, v237
	v_fmamk_f32 v87, v87, 0x3e38aa3b, v237
	s_waitcnt lgkmcnt(0)
	ds_read_b64_tr_b16 v[192:193], v146 offset:0x2000
	ds_read_b64_tr_b16 v[194:195], v146 offset:0x2800
	ds_read_b64_tr_b16 v[196:197], v146 offset:0x2200
	ds_read_b64_tr_b16 v[198:199], v146 offset:0x2a00
	ds_read_b64_tr_b16 v[200:201], v146 offset:0x2400
	ds_read_b64_tr_b16 v[202:203], v146 offset:0x2c00
	ds_read_b64_tr_b16 v[204:205], v146 offset:0x2600
	ds_read_b64_tr_b16 v[206:207], v146 offset:0x2e00
	ds_read_b64_tr_b16 v[210:211], v146 offset:0x3000
	ds_read_b64_tr_b16 v[212:213], v146 offset:0x3800
	ds_read_b64_tr_b16 v[214:215], v146 offset:0x3200
	ds_read_b64_tr_b16 v[216:217], v146 offset:0x3a00
	ds_read_b64_tr_b16 v[218:219], v146 offset:0x3400
	ds_read_b64_tr_b16 v[220:221], v146 offset:0x3c00
	ds_read_b64_tr_b16 v[222:223], v146 offset:0x3600
	ds_read_b64_tr_b16 v[224:225], v146 offset:0x3e00
	v_mfma_f32_32x32x16_bf16 v[0:15], v[96:99], v[104:107], v[0:15]
	v_fmamk_f32 v88, v88, 0x3e38aa3b, v237
	v_fmamk_f32 v89, v89, 0x3e38aa3b, v237
	v_fmamk_f32 v90, v90, 0x3e38aa3b, v237
	v_fmamk_f32 v91, v91, 0x3e38aa3b, v237
	v_fmamk_f32 v92, v92, 0x3e38aa3b, v237
	v_fmamk_f32 v93, v93, 0x3e38aa3b, v237
	v_fmamk_f32 v94, v94, 0x3e38aa3b, v237
	v_fmac_f32_e32 v237, 0x3e38aa3b, v95
	v_fmamk_f32 v64, v64, 0x3e38aa3b, v236
	v_fmamk_f32 v65, v65, 0x3e38aa3b, v236
	v_fmamk_f32 v66, v66, 0x3e38aa3b, v236
	v_fmamk_f32 v67, v67, 0x3e38aa3b, v236
	v_fmamk_f32 v68, v68, 0x3e38aa3b, v236
	v_fmamk_f32 v69, v69, 0x3e38aa3b, v236
	v_fmamk_f32 v70, v70, 0x3e38aa3b, v236
	v_mfma_f32_32x32x16_bf16 v[16:31], v[96:99], v[108:111], v[16:31]
	v_fmamk_f32 v71, v71, 0x3e38aa3b, v236
	v_fmamk_f32 v72, v72, 0x3e38aa3b, v236
	v_fmamk_f32 v73, v73, 0x3e38aa3b, v236
	v_fmamk_f32 v74, v74, 0x3e38aa3b, v236
	v_fmamk_f32 v75, v75, 0x3e38aa3b, v236
	v_fmamk_f32 v76, v76, 0x3e38aa3b, v236
	v_fmamk_f32 v77, v77, 0x3e38aa3b, v236
	v_fmamk_f32 v78, v78, 0x3e38aa3b, v236
	v_fmac_f32_e32 v236, 0x3e38aa3b, v79
	v_exp_f32_e32 v80, v80
	v_exp_f32_e32 v81, v81
	v_exp_f32_e32 v82, v82
	v_mfma_f32_32x32x16_bf16 v[32:47], v[96:99], v[112:115], v[32:47]
	v_exp_f32_e32 v83, v83
	v_exp_f32_e32 v84, v84
	v_exp_f32_e32 v85, v85
	v_exp_f32_e32 v86, v86
	v_exp_f32_e32 v87, v87
	v_exp_f32_e32 v88, v88
	v_exp_f32_e32 v89, v89
	v_mfma_f32_32x32x16_bf16 v[48:63], v[96:99], v[116:119], v[48:63]
	v_exp_f32_e32 v90, v90
	v_exp_f32_e32 v91, v91
	v_exp_f32_e32 v92, v92
	v_exp_f32_e32 v93, v93
	v_exp_f32_e32 v94, v94
	v_exp_f32_e32 v95, v237
	v_exp_f32_e32 v64, v64
	v_mfma_f32_32x32x16_bf16 v[0:15], v[100:103], v[238:241], v[0:15]
	v_exp_f32_e32 v65, v65
	v_exp_f32_e32 v66, v66
	v_exp_f32_e32 v67, v67
	v_exp_f32_e32 v68, v68
	v_exp_f32_e32 v69, v69
	v_exp_f32_e32 v70, v70
	v_exp_f32_e32 v71, v71
	v_mfma_f32_32x32x16_bf16 v[16:31], v[100:103], v[242:245], v[16:31]
	v_exp_f32_e32 v72, v72
	v_exp_f32_e32 v73, v73
	v_exp_f32_e32 v74, v74
	v_exp_f32_e32 v75, v75
	v_exp_f32_e32 v76, v76
	v_exp_f32_e32 v77, v77
	v_exp_f32_e32 v78, v78
	v_mfma_f32_32x32x16_bf16 v[32:47], v[100:103], v[246:249], v[32:47]
	v_exp_f32_e32 v79, v236
	v_pk_fma_f32 v[64:65], v[144:145], v[64:65], v[80:81]
	v_pk_fma_f32 v[66:67], v[144:145], v[66:67], v[82:83]
	v_pk_fma_f32 v[68:69], v[144:145], v[68:69], v[84:85]
	v_pk_fma_f32 v[70:71], v[144:145], v[70:71], v[86:87]
	v_pk_fma_f32 v[72:73], v[144:145], v[72:73], v[88:89]
	v_pk_fma_f32 v[74:75], v[144:145], v[74:75], v[90:91]
	v_mfma_f32_32x32x16_bf16 v[48:63], v[100:103], v[120:123], v[48:63]
	v_pk_fma_f32 v[76:77], v[144:145], v[76:77], v[92:93]
	v_pk_fma_f32 v[78:79], v[144:145], v[78:79], v[94:95]
	v_cvt_pk_bf16_f32 v64, v64, v65
	v_cvt_pk_bf16_f32 v65, v66, v67
	v_cvt_pk_bf16_f32 v66, v68, v69
	v_cvt_pk_bf16_f32 v67, v70, v71
	v_cvt_pk_bf16_f32 v68, v72, v73
	v_cvt_pk_bf16_f32 v69, v74, v75
	v_cvt_pk_bf16_f32 v70, v76, v77
	v_cvt_pk_bf16_f32 v71, v78, v79
	v_permlane32_swap_b32_e32 v64, v66
	v_permlane32_swap_b32_e32 v65, v67
	v_permlane32_swap_b32_e32 v68, v70
	v_permlane32_swap_b32_e32 v69, v71
	s_waitcnt lgkmcnt(0)
	v_mfma_f32_32x32x16_bf16 v[0:15], v[64:67], v[192:195], v[0:15]
	v_mfma_f32_32x32x16_bf16 v[16:31], v[64:67], v[196:199], v[16:31]
	v_mfma_f32_32x32x16_bf16 v[32:47], v[64:67], v[200:203], v[32:47]
	v_mfma_f32_32x32x16_bf16 v[48:63], v[64:67], v[204:207], v[48:63]
	v_mfma_f32_32x32x16_bf16 v[0:15], v[68:71], v[210:213], v[0:15]
	s_add_u32 s34, s34, 0x20000
	s_addc_u32 s35, s35, 0
	v_add_u32_e32 v173, 64, v173
	s_add_i32 s93, s93, 64
	s_cmp_eq_u32 s2, s34
	v_mfma_f32_32x32x16_bf16 v[16:31], v[68:71], v[214:217], v[16:31]
	v_mfma_f32_32x32x16_bf16 v[32:47], v[68:71], v[218:221], v[32:47]
	v_mfma_f32_32x32x16_bf16 v[48:63], v[68:71], v[222:225], v[48:63]
	s_cbranch_scc1 .LBB0_326
	s_branch .LBB0_310
